# baseline (speedup 1.0000x reference)
; __device__ __forceinline__ float bflo(unsigned v) { return __uint_as_float(v << 16); }
; __device__ __forceinline__ float bfhi(unsigned v) { return __uint_as_float(v & 0xffff0000u); }
; __device__ __forceinline__ void phase4(const Params& p, char* shm) {
;     ...
;       GEMM_IDS;
;       char* const cfb = CF_BASE(shm);
;       const u16* gsrc = Gates + (brow + ai * 128) * 4096 + bcol;
; #pragma unroll
;       for (int b8 = 0; b8 < 2; ++b8) {
;         u32x2 ga[8], gb[8];
; #pragma unroll
;         for (int i = 0; i < 8; ++i) { const int id = tid + (b8 * 8 + i) * NTHR, row = id >> 6, c = id & 63;
;           ga[i] = *reinterpret_cast<const u32x2*>(gsrc + (size_t)row * 4096 + c * 4);
;           gb[i] = *reinterpret_cast<const u32x2*>(gsrc + (size_t)row * 4096 + 2048 + c * 4); }
; #pragma unroll
;         for (int i = 0; i < 8; ++i) { const int id = tid + (b8 * 8 + i) * NTHR, row = id >> 6, c = id & 63;
;           f32x4 rt = { bflo(ga[i][0]) * __builtin_amdgcn_rcpf(bflo(gb[i][0])), bfhi(ga[i][0]) * __builtin_amdgcn_rcpf(bfhi(gb[i][0])),
;                        bflo(ga[i][1]) * __builtin_amdgcn_rcpf(bflo(gb[i][1])), bfhi(ga[i][1]) * __builtin_amdgcn_rcpf(bfhi(gb[i][1])) };
;           *reinterpret_cast<f32x4*>(shm + (row * CF_LD + c * 4) * 4) = rt; }
.LBB0_457:
	s_or_b64 exec, exec, s[30:31]
	s_andn2_b64 vcc, exec, s[20:21]
	s_barrier
	s_cbranch_vccnz .LBB0_450
	v_mov_b32_e32 v187, v1
	s_nop 0
	v_and_b32_e32 v2, 15, v187
	v_lshrrev_b32_e32 v4, 2, v187
	v_and_or_b32 v2, v4, s51, v2
	v_mul_lo_u32 v5, v2, s52
	v_lshrrev_b32_e32 v2, 1, v187
	v_ashrrev_i32_e32 v140, 6, v187
	v_and_b32_e32 v134, 0x60, v2
	v_lshlrev_b32_e32 v2, 2, v187
	v_ashrrev_i32_e32 v141, 31, v140
	v_and_b32_e32 v4, 0xfc, v2
	v_lshlrev_b64 v[136:137], 13, v[140:141]
	v_lshl_add_u64 v[136:137], s[12:13], 0, v[136:137]
	v_lshlrev_b32_e32 v2, 1, v4
	v_lshl_add_u64 v[136:137], v[136:137], 0, v[2:3]
	v_add_co_u32_e32 v138, vcc, s49, v136
	v_add_u32_e32 v141, 0x600, v187
	s_nop 0
	v_addc_co_u32_e32 v139, vcc, 0, v137, vcc
	global_load_dwordx2 v[142:143], v[136:137], off
	s_nop 0
	global_load_dwordx2 v[136:137], v[138:139], off
	v_add_u32_e32 v138, 0x200, v187
	v_ashrrev_i32_e32 v144, 6, v138
	v_ashrrev_i32_e32 v145, 31, v144
	v_lshlrev_b64 v[138:139], 13, v[144:145]
	v_lshl_add_u64 v[138:139], s[12:13], 0, v[138:139]
	v_lshl_add_u64 v[138:139], v[138:139], 0, v[2:3]
	v_add_co_u32_e32 v146, vcc, s49, v138
	v_ashrrev_i32_e32 v154, 6, v141
	s_nop 0
	v_addc_co_u32_e32 v147, vcc, 0, v139, vcc
	global_load_dwordx2 v[148:149], v[138:139], off
	s_nop 0
	global_load_dwordx2 v[146:147], v[146:147], off
	v_add_u32_e32 v138, 0x400, v187
	v_ashrrev_i32_e32 v150, 6, v138
	v_ashrrev_i32_e32 v151, 31, v150
	v_lshlrev_b64 v[138:139], 13, v[150:151]
	v_lshl_add_u64 v[138:139], s[12:13], 0, v[138:139]
	v_ashrrev_i32_e32 v155, 31, v154
	v_lshl_add_u64 v[138:139], v[138:139], 0, v[2:3]
	v_lshlrev_b64 v[156:157], 13, v[154:155]
	v_add_co_u32_e32 v152, vcc, s49, v138
	v_lshl_add_u64 v[156:157], s[12:13], 0, v[156:157]
	s_nop 0
	v_addc_co_u32_e32 v153, vcc, 0, v139, vcc
	v_lshl_add_u64 v[156:157], v[156:157], 0, v[2:3]
	v_add_co_u32_e32 v158, vcc, s49, v156
	v_add_u32_e32 v141, 0xa00, v187
	s_nop 0
	v_addc_co_u32_e32 v159, vcc, 0, v157, vcc
	global_load_dwordx2 v[160:161], v[138:139], off
	s_nop 0
	global_load_dwordx2 v[152:153], v[152:153], off
	s_nop 0
	global_load_dwordx2 v[156:157], v[156:157], off
	s_nop 0
	global_load_dwordx2 v[158:159], v[158:159], off
	v_add_u32_e32 v138, 0x800, v187
	v_ashrrev_i32_e32 v162, 6, v138
	v_ashrrev_i32_e32 v163, 31, v162
	v_lshlrev_b64 v[138:139], 13, v[162:163]
	v_ashrrev_i32_e32 v166, 6, v141
	v_lshl_add_u64 v[138:139], s[12:13], 0, v[138:139]
	v_ashrrev_i32_e32 v167, 31, v166
	v_lshl_add_u64 v[138:139], v[138:139], 0, v[2:3]
	v_lshlrev_b64 v[168:169], 13, v[166:167]
	v_add_co_u32_e32 v164, vcc, s49, v138
	v_lshl_add_u64 v[168:169], s[12:13], 0, v[168:169]
	s_nop 0
	v_addc_co_u32_e32 v165, vcc, 0, v139, vcc
	v_lshl_add_u64 v[168:169], v[168:169], 0, v[2:3]
	v_add_co_u32_e32 v170, vcc, s49, v168
	v_add_u32_e32 v141, 0xe00, v187
	s_nop 0
	v_addc_co_u32_e32 v171, vcc, 0, v169, vcc
	global_load_dwordx2 v[172:173], v[138:139], off
	s_nop 0
	global_load_dwordx2 v[164:165], v[164:165], off
	s_nop 0
	global_load_dwordx2 v[168:169], v[168:169], off
	s_nop 0
	global_load_dwordx2 v[170:171], v[170:171], off
	v_add_u32_e32 v138, 0xc00, v187
	v_ashrrev_i32_e32 v174, 6, v138
	v_ashrrev_i32_e32 v175, 31, v174
	v_lshlrev_b64 v[138:139], 13, v[174:175]
	v_ashrrev_i32_e32 v178, 6, v141
	v_lshl_add_u64 v[138:139], s[12:13], 0, v[138:139]
	v_ashrrev_i32_e32 v179, 31, v178
	v_lshl_add_u64 v[138:139], v[138:139], 0, v[2:3]
	v_lshlrev_b64 v[180:181], 13, v[178:179]
	v_add_co_u32_e32 v176, vcc, s49, v138
	v_lshl_add_u64 v[180:181], s[12:13], 0, v[180:181]
	s_nop 0
	v_addc_co_u32_e32 v177, vcc, 0, v139, vcc
	v_lshl_add_u64 v[180:181], v[180:181], 0, v[2:3]
	v_add_co_u32_e32 v182, vcc, s49, v180
	v_mad_u64_u32 v[140:141], s[20:21], v140, s52, v[4:5]
	s_nop 0
	v_addc_co_u32_e32 v183, vcc, 0, v181, vcc
	global_load_dwordx2 v[184:185], v[138:139], off
	s_nop 0
	global_load_dwordx2 v[176:177], v[176:177], off
	s_nop 0
	global_load_dwordx2 v[180:181], v[180:181], off
	s_nop 0
	global_load_dwordx2 v[182:183], v[182:183], off
	v_add_u32_e32 v198, 0x1000, v187
	v_ashrrev_i32_e32 v202, 6, v198
	v_ashrrev_i32_e32 v203, 31, v202
	v_lshlrev_b64 v[198:199], 13, v[202:203]
	v_lshl_add_u64 v[198:199], s[12:13], 0, v[198:199]
	v_lshl_add_u64 v[198:199], v[198:199], 0, v[2:3]
	v_add_co_u32_e32 v200, vcc, s49, v198
	v_add_u32_e32 v203, 0x1600, v187
	s_nop 0
	v_addc_co_u32_e32 v201, vcc, 0, v199, vcc
	global_load_dwordx2 v[204:205], v[198:199], off
	s_nop 0
	global_load_dwordx2 v[198:199], v[200:201], off
	v_add_u32_e32 v200, 0x1200, v187
	v_ashrrev_i32_e32 v206, 6, v200
	v_ashrrev_i32_e32 v207, 31, v206
	v_lshlrev_b64 v[200:201], 13, v[206:207]
	v_lshl_add_u64 v[200:201], s[12:13], 0, v[200:201]
	v_lshl_add_u64 v[200:201], v[200:201], 0, v[2:3]
	v_add_co_u32_e32 v208, vcc, s49, v200
	v_ashrrev_i32_e32 v216, 6, v203
	s_nop 0
	v_addc_co_u32_e32 v209, vcc, 0, v201, vcc
	global_load_dwordx2 v[210:211], v[200:201], off
	s_nop 0
	global_load_dwordx2 v[208:209], v[208:209], off
	v_add_u32_e32 v200, 0x1400, v187
	v_ashrrev_i32_e32 v212, 6, v200
	v_ashrrev_i32_e32 v213, 31, v212
	v_lshlrev_b64 v[200:201], 13, v[212:213]
	v_lshl_add_u64 v[200:201], s[12:13], 0, v[200:201]
	v_ashrrev_i32_e32 v217, 31, v216
	v_lshl_add_u64 v[200:201], v[200:201], 0, v[2:3]
	v_lshlrev_b64 v[218:219], 13, v[216:217]
	v_add_co_u32_e32 v214, vcc, s49, v200
	v_lshl_add_u64 v[218:219], s[12:13], 0, v[218:219]
	s_nop 0
	v_addc_co_u32_e32 v215, vcc, 0, v201, vcc
	v_lshl_add_u64 v[218:219], v[218:219], 0, v[2:3]
	v_add_co_u32_e32 v220, vcc, s49, v218
	v_add_u32_e32 v203, 0x1a00, v187
	s_nop 0
	v_addc_co_u32_e32 v221, vcc, 0, v219, vcc
	global_load_dwordx2 v[222:223], v[200:201], off
; __device__ __forceinline__ float bflo(unsigned v) { return __uint_as_float(v << 16); }
; __device__ __forceinline__ float bfhi(unsigned v) { return __uint_as_float(v & 0xffff0000u); }
; __device__ __forceinline__ void phase4(const Params& p, char* shm) {
;     ...
;       for (int b8 = 0; b8 < 2; ++b8) {
;         u32x2 ga[8], gb[8];
; #pragma unroll
;         for (int i = 0; i < 8; ++i) { const int id = tid + (b8 * 8 + i) * NTHR, row = id >> 6, c = id & 63;
;           ga[i] = *reinterpret_cast<const u32x2*>(gsrc + (size_t)row * 4096 + c * 4);
;           gb[i] = *reinterpret_cast<const u32x2*>(gsrc + (size_t)row * 4096 + 2048 + c * 4); }
; #pragma unroll
;         for (int i = 0; i < 8; ++i) { const int id = tid + (b8 * 8 + i) * NTHR, row = id >> 6, c = id & 63;
;           f32x4 rt = { bflo(ga[i][0]) * __builtin_amdgcn_rcpf(bflo(gb[i][0])), bfhi(ga[i][0]) * __builtin_amdgcn_rcpf(bfhi(gb[i][0])),
;                        bflo(ga[i][1]) * __builtin_amdgcn_rcpf(bflo(gb[i][1])), bfhi(ga[i][1]) * __builtin_amdgcn_rcpf(bfhi(gb[i][1])) };
;           *reinterpret_cast<f32x4*>(shm + (row * CF_LD + c * 4) * 4) = rt; }
	s_nop 0
	global_load_dwordx2 v[214:215], v[214:215], off
	s_nop 0
	global_load_dwordx2 v[218:219], v[218:219], off
	s_nop 0
	global_load_dwordx2 v[220:221], v[220:221], off
	v_add_u32_e32 v200, 0x1800, v187
	v_ashrrev_i32_e32 v224, 6, v200
	v_ashrrev_i32_e32 v225, 31, v224
	v_lshlrev_b64 v[200:201], 13, v[224:225]
	v_ashrrev_i32_e32 v228, 6, v203
	v_lshl_add_u64 v[200:201], s[12:13], 0, v[200:201]
	v_ashrrev_i32_e32 v229, 31, v228
	v_lshl_add_u64 v[200:201], v[200:201], 0, v[2:3]
	v_lshlrev_b64 v[230:231], 13, v[228:229]
	v_add_co_u32_e32 v226, vcc, s49, v200
	v_lshl_add_u64 v[230:231], s[12:13], 0, v[230:231]
	s_nop 0
	v_addc_co_u32_e32 v227, vcc, 0, v201, vcc
	v_lshl_add_u64 v[230:231], v[230:231], 0, v[2:3]
	v_add_co_u32_e32 v232, vcc, s49, v230
	v_add_u32_e32 v203, 0x1e00, v187
	s_nop 0
	v_addc_co_u32_e32 v233, vcc, 0, v231, vcc
	global_load_dwordx2 v[234:235], v[200:201], off
	s_nop 0
	global_load_dwordx2 v[226:227], v[226:227], off
	s_nop 0
	global_load_dwordx2 v[230:231], v[230:231], off
	s_nop 0
	global_load_dwordx2 v[232:233], v[232:233], off
	v_add_u32_e32 v200, 0x1c00, v187
	v_ashrrev_i32_e32 v236, 6, v200
	v_ashrrev_i32_e32 v237, 31, v236
	v_lshlrev_b64 v[200:201], 13, v[236:237]
	v_ashrrev_i32_e32 v240, 6, v203
	v_lshl_add_u64 v[200:201], s[12:13], 0, v[200:201]
	v_ashrrev_i32_e32 v241, 31, v240
	v_lshl_add_u64 v[200:201], v[200:201], 0, v[2:3]
	v_lshlrev_b64 v[242:243], 13, v[240:241]
	v_add_co_u32_e32 v238, vcc, s49, v200
	v_lshl_add_u64 v[242:243], s[12:13], 0, v[242:243]
	s_nop 0
	v_addc_co_u32_e32 v239, vcc, 0, v201, vcc
	v_lshl_add_u64 v[242:243], v[242:243], 0, v[2:3]
	v_add_co_u32_e32 v244, vcc, s49, v242
	v_mad_u64_u32 v[202:203], s[20:21], v202, s52, v[4:5]
	s_nop 0
	v_addc_co_u32_e32 v245, vcc, 0, v243, vcc
	global_load_dwordx2 v[246:247], v[200:201], off
	s_nop 0
	global_load_dwordx2 v[238:239], v[238:239], off
	s_nop 0
	global_load_dwordx2 v[242:243], v[242:243], off
	s_nop 0
	global_load_dwordx2 v[244:245], v[244:245], off
	v_lshl_add_u32 v140, v140, 2, 0
	v_and_b32_e32 v135, 48, v187
	s_waitcnt vmcnt(31)
	v_lshlrev_b32_e32 v188, 16, v142
	s_waitcnt vmcnt(30)
	v_lshlrev_b32_e32 v138, 16, v136
	v_and_b32_e32 v136, 0xffff0000, v136
	v_rcp_f32_e32 v139, v136
	v_lshlrev_b32_e32 v136, 16, v137
	v_rcp_f32_e32 v138, v138
	v_rcp_f32_e32 v190, v136
	v_and_b32_e32 v136, 0xffff0000, v137
	v_rcp_f32_e32 v191, v136
	v_and_b32_e32 v189, 0xffff0000, v142
	v_pk_mul_f32 v[136:137], v[138:139], v[188:189]
	v_lshlrev_b32_e32 v138, 16, v143
	v_and_b32_e32 v139, 0xffff0000, v143
	v_pk_mul_f32 v[138:139], v[190:191], v[138:139]
	ds_write_b128 v140, v[136:139]
	s_waitcnt vmcnt(28)
	v_lshlrev_b32_e32 v136, 16, v146
	v_and_b32_e32 v137, 0xffff0000, v146
	v_rcp_f32_e32 v136, v136
	v_rcp_f32_e32 v137, v137
	v_lshlrev_b32_e32 v140, 16, v147
	v_and_b32_e32 v141, 0xffff0000, v147
	v_rcp_f32_e32 v140, v140
	v_rcp_f32_e32 v141, v141
	v_lshlrev_b32_e32 v138, 16, v148
	v_and_b32_e32 v139, 0xffff0000, v148
	v_pk_mul_f32 v[136:137], v[136:137], v[138:139]
	v_lshlrev_b32_e32 v138, 16, v149
	v_and_b32_e32 v139, 0xffff0000, v149
	v_pk_mul_f32 v[138:139], v[140:141], v[138:139]
	v_mad_u64_u32 v[140:141], s[20:21], v144, s52, v[4:5]
	v_lshl_add_u32 v140, v140, 2, 0
	ds_write_b128 v140, v[136:139]
	s_waitcnt vmcnt(26)
	v_lshlrev_b32_e32 v136, 16, v152
	v_and_b32_e32 v137, 0xffff0000, v152
	v_rcp_f32_e32 v136, v136
	v_rcp_f32_e32 v137, v137
	v_lshlrev_b32_e32 v140, 16, v153
	v_and_b32_e32 v141, 0xffff0000, v153
	v_rcp_f32_e32 v140, v140
	v_rcp_f32_e32 v141, v141
	v_lshlrev_b32_e32 v138, 16, v160
	v_and_b32_e32 v139, 0xffff0000, v160
	v_pk_mul_f32 v[136:137], v[136:137], v[138:139]
	v_lshlrev_b32_e32 v138, 16, v161
	v_and_b32_e32 v139, 0xffff0000, v161
	v_pk_mul_f32 v[138:139], v[140:141], v[138:139]
	v_mad_u64_u32 v[140:141], s[20:21], v150, s52, v[4:5]
	v_lshl_add_u32 v140, v140, 2, 0
	ds_write_b128 v140, v[136:139]
	s_waitcnt vmcnt(24)
	v_lshlrev_b32_e32 v136, 16, v158
	v_and_b32_e32 v137, 0xffff0000, v158
	v_rcp_f32_e32 v136, v136
	v_rcp_f32_e32 v137, v137
	v_lshlrev_b32_e32 v140, 16, v159
	v_and_b32_e32 v141, 0xffff0000, v159
	v_rcp_f32_e32 v140, v140
	v_rcp_f32_e32 v141, v141
	v_lshlrev_b32_e32 v138, 16, v156
	v_and_b32_e32 v139, 0xffff0000, v156
	v_pk_mul_f32 v[136:137], v[136:137], v[138:139]
	v_lshlrev_b32_e32 v138, 16, v157
	v_and_b32_e32 v139, 0xffff0000, v157
	v_pk_mul_f32 v[138:139], v[140:141], v[138:139]
	v_mad_u64_u32 v[140:141], s[20:21], v154, s52, v[4:5]
	v_lshl_add_u32 v140, v140, 2, 0
	ds_write_b128 v140, v[136:139]
	s_waitcnt vmcnt(22)
	v_lshlrev_b32_e32 v136, 16, v164
	v_and_b32_e32 v137, 0xffff0000, v164
	v_rcp_f32_e32 v136, v136
	v_rcp_f32_e32 v137, v137
	v_lshlrev_b32_e32 v140, 16, v165
	v_and_b32_e32 v141, 0xffff0000, v165
	v_rcp_f32_e32 v140, v140
	v_rcp_f32_e32 v141, v141
	v_lshlrev_b32_e32 v138, 16, v172
	v_and_b32_e32 v139, 0xffff0000, v172
	v_pk_mul_f32 v[136:137], v[136:137], v[138:139]
	v_lshlrev_b32_e32 v138, 16, v173
	v_and_b32_e32 v139, 0xffff0000, v173
	v_pk_mul_f32 v[138:139], v[140:141], v[138:139]
	v_mad_u64_u32 v[140:141], s[20:21], v162, s52, v[4:5]
	v_lshl_add_u32 v140, v140, 2, 0
	ds_write_b128 v140, v[136:139]
	s_waitcnt vmcnt(20)
	v_lshlrev_b32_e32 v136, 16, v170
	v_and_b32_e32 v137, 0xffff0000, v170
	v_rcp_f32_e32 v136, v136
	v_rcp_f32_e32 v137, v137
	v_lshlrev_b32_e32 v140, 16, v171
	v_and_b32_e32 v141, 0xffff0000, v171
	v_rcp_f32_e32 v140, v140
	v_rcp_f32_e32 v141, v141
	v_lshlrev_b32_e32 v138, 16, v168
	v_and_b32_e32 v139, 0xffff0000, v168
	v_pk_mul_f32 v[136:137], v[136:137], v[138:139]
	v_lshlrev_b32_e32 v138, 16, v169
	v_and_b32_e32 v139, 0xffff0000, v169
	v_pk_mul_f32 v[138:139], v[140:141], v[138:139]
	v_mad_u64_u32 v[140:141], s[20:21], v166, s52, v[4:5]
	v_lshl_add_u32 v140, v140, 2, 0
	ds_write_b128 v140, v[136:139]
	s_waitcnt vmcnt(18)
; __device__ __forceinline__ float bflo(unsigned v) { return __uint_as_float(v << 16); }
; __device__ __forceinline__ float bfhi(unsigned v) { return __uint_as_float(v & 0xffff0000u); }
; __device__ __forceinline__ void phase4(const Params& p, char* shm) {
;     ...
;       for (int b8 = 0; b8 < 2; ++b8) {
;         u32x2 ga[8], gb[8];
; #pragma unroll
;         for (int i = 0; i < 8; ++i) { const int id = tid + (b8 * 8 + i) * NTHR, row = id >> 6, c = id & 63;
;           ga[i] = *reinterpret_cast<const u32x2*>(gsrc + (size_t)row * 4096 + c * 4);
;           gb[i] = *reinterpret_cast<const u32x2*>(gsrc + (size_t)row * 4096 + 2048 + c * 4); }
; #pragma unroll
;         for (int i = 0; i < 8; ++i) { const int id = tid + (b8 * 8 + i) * NTHR, row = id >> 6, c = id & 63;
;           f32x4 rt = { bflo(ga[i][0]) * __builtin_amdgcn_rcpf(bflo(gb[i][0])), bfhi(ga[i][0]) * __builtin_amdgcn_rcpf(bfhi(gb[i][0])),
;                        bflo(ga[i][1]) * __builtin_amdgcn_rcpf(bflo(gb[i][1])), bfhi(ga[i][1]) * __builtin_amdgcn_rcpf(bfhi(gb[i][1])) };
;           *reinterpret_cast<f32x4*>(shm + (row * CF_LD + c * 4) * 4) = rt; }
	v_lshlrev_b32_e32 v136, 16, v176
	v_and_b32_e32 v137, 0xffff0000, v176
	v_rcp_f32_e32 v136, v136
	v_rcp_f32_e32 v137, v137
	v_lshlrev_b32_e32 v140, 16, v177
	v_and_b32_e32 v141, 0xffff0000, v177
	v_rcp_f32_e32 v140, v140
	v_rcp_f32_e32 v141, v141
	v_lshlrev_b32_e32 v138, 16, v184
	v_and_b32_e32 v139, 0xffff0000, v184
	v_pk_mul_f32 v[136:137], v[136:137], v[138:139]
	v_lshlrev_b32_e32 v138, 16, v185
	v_and_b32_e32 v139, 0xffff0000, v185
	v_pk_mul_f32 v[138:139], v[140:141], v[138:139]
	v_mad_u64_u32 v[140:141], s[20:21], v174, s52, v[4:5]
	v_lshl_add_u32 v140, v140, 2, 0
	ds_write_b128 v140, v[136:139]
	s_waitcnt vmcnt(16)
	v_lshlrev_b32_e32 v136, 16, v182
	v_and_b32_e32 v137, 0xffff0000, v182
	v_rcp_f32_e32 v136, v136
	v_rcp_f32_e32 v137, v137
	v_lshlrev_b32_e32 v140, 16, v183
	v_and_b32_e32 v141, 0xffff0000, v183
	v_rcp_f32_e32 v140, v140
	v_rcp_f32_e32 v141, v141
	v_lshlrev_b32_e32 v138, 16, v180
	v_and_b32_e32 v139, 0xffff0000, v180
	v_pk_mul_f32 v[136:137], v[136:137], v[138:139]
	v_lshlrev_b32_e32 v138, 16, v181
	v_and_b32_e32 v139, 0xffff0000, v181
	v_pk_mul_f32 v[138:139], v[140:141], v[138:139]
	v_mad_u64_u32 v[140:141], s[20:21], v178, s52, v[4:5]
	v_lshl_add_u32 v140, v140, 2, 0
	ds_write_b128 v140, v[136:139]
	v_mov_b32_e32 v187, v1
	s_waitcnt vmcnt(15)
	v_lshlrev_b32_e32 v248, 16, v204
	s_waitcnt vmcnt(14)
	v_lshlrev_b32_e32 v2, 16, v198
	v_rcp_f32_e32 v200, v2
	v_and_b32_e32 v2, 0xffff0000, v198
	v_rcp_f32_e32 v201, v2
	v_lshlrev_b32_e32 v2, 16, v199
	v_rcp_f32_e32 v250, v2
	v_and_b32_e32 v2, 0xffff0000, v199
	v_rcp_f32_e32 v251, v2
	v_and_b32_e32 v249, 0xffff0000, v204
	v_pk_mul_f32 v[198:199], v[200:201], v[248:249]
	v_lshlrev_b32_e32 v200, 16, v205
	v_and_b32_e32 v201, 0xffff0000, v205
	v_pk_mul_f32 v[200:201], v[250:251], v[200:201]
	v_lshl_add_u32 v2, v202, 2, 0
	ds_write_b128 v2, v[198:201]
	s_waitcnt vmcnt(12)
	v_lshlrev_b32_e32 v2, 16, v208
	v_rcp_f32_e32 v198, v2
	v_and_b32_e32 v2, 0xffff0000, v208
	v_rcp_f32_e32 v199, v2
	v_lshlrev_b32_e32 v2, 16, v209
	v_rcp_f32_e32 v202, v2
	v_and_b32_e32 v2, 0xffff0000, v209
	v_rcp_f32_e32 v203, v2
	v_lshlrev_b32_e32 v200, 16, v210
	v_and_b32_e32 v201, 0xffff0000, v210
	v_pk_mul_f32 v[198:199], v[198:199], v[200:201]
	v_lshlrev_b32_e32 v200, 16, v211
	v_and_b32_e32 v201, 0xffff0000, v211
	v_pk_mul_f32 v[200:201], v[202:203], v[200:201]
	v_mad_u64_u32 v[202:203], s[20:21], v206, s52, v[4:5]
	v_lshl_add_u32 v2, v202, 2, 0
	ds_write_b128 v2, v[198:201]
	s_waitcnt vmcnt(10)
	v_lshlrev_b32_e32 v2, 16, v214
	v_rcp_f32_e32 v198, v2
	v_and_b32_e32 v2, 0xffff0000, v214
	v_rcp_f32_e32 v199, v2
	v_lshlrev_b32_e32 v2, 16, v215
	v_rcp_f32_e32 v202, v2
	v_and_b32_e32 v2, 0xffff0000, v215
	v_rcp_f32_e32 v203, v2
	v_lshlrev_b32_e32 v200, 16, v222
	v_and_b32_e32 v201, 0xffff0000, v222
	v_pk_mul_f32 v[198:199], v[198:199], v[200:201]
	v_lshlrev_b32_e32 v200, 16, v223
	v_and_b32_e32 v201, 0xffff0000, v223
	v_pk_mul_f32 v[200:201], v[202:203], v[200:201]
	v_mad_u64_u32 v[202:203], s[20:21], v212, s52, v[4:5]
	v_lshl_add_u32 v2, v202, 2, 0
	ds_write_b128 v2, v[198:201]
	s_waitcnt vmcnt(8)
	v_lshlrev_b32_e32 v2, 16, v220
	v_rcp_f32_e32 v198, v2
	v_and_b32_e32 v2, 0xffff0000, v220
	v_rcp_f32_e32 v199, v2
	v_lshlrev_b32_e32 v2, 16, v221
	v_rcp_f32_e32 v202, v2
	v_and_b32_e32 v2, 0xffff0000, v221
	v_rcp_f32_e32 v203, v2
	v_lshlrev_b32_e32 v200, 16, v218
	v_and_b32_e32 v201, 0xffff0000, v218
	v_pk_mul_f32 v[198:199], v[198:199], v[200:201]
	v_lshlrev_b32_e32 v200, 16, v219
	v_and_b32_e32 v201, 0xffff0000, v219
	v_pk_mul_f32 v[200:201], v[202:203], v[200:201]
	v_mad_u64_u32 v[202:203], s[20:21], v216, s52, v[4:5]
	v_lshl_add_u32 v2, v202, 2, 0
	ds_write_b128 v2, v[198:201]
	s_waitcnt vmcnt(6)
	v_lshlrev_b32_e32 v2, 16, v226
	v_rcp_f32_e32 v198, v2
	v_and_b32_e32 v2, 0xffff0000, v226
	v_rcp_f32_e32 v199, v2
	v_lshlrev_b32_e32 v2, 16, v227
	v_rcp_f32_e32 v202, v2
	v_and_b32_e32 v2, 0xffff0000, v227
	v_rcp_f32_e32 v203, v2
	v_lshlrev_b32_e32 v200, 16, v234
	v_and_b32_e32 v201, 0xffff0000, v234
	v_pk_mul_f32 v[198:199], v[198:199], v[200:201]
	v_lshlrev_b32_e32 v200, 16, v235
	v_and_b32_e32 v201, 0xffff0000, v235
	v_pk_mul_f32 v[200:201], v[202:203], v[200:201]
	v_mad_u64_u32 v[202:203], s[20:21], v224, s52, v[4:5]
	v_lshl_add_u32 v2, v202, 2, 0
	ds_write_b128 v2, v[198:201]
	s_waitcnt vmcnt(4)
	v_lshlrev_b32_e32 v2, 16, v232
	v_rcp_f32_e32 v198, v2
	v_and_b32_e32 v2, 0xffff0000, v232
	v_rcp_f32_e32 v199, v2
	v_lshlrev_b32_e32 v2, 16, v233
	v_rcp_f32_e32 v202, v2
	v_and_b32_e32 v2, 0xffff0000, v233
	v_rcp_f32_e32 v203, v2
	v_lshlrev_b32_e32 v200, 16, v230
	v_and_b32_e32 v201, 0xffff0000, v230
	v_pk_mul_f32 v[198:199], v[198:199], v[200:201]
	v_lshlrev_b32_e32 v200, 16, v231
	v_and_b32_e32 v201, 0xffff0000, v231
	v_pk_mul_f32 v[200:201], v[202:203], v[200:201]
	v_mad_u64_u32 v[202:203], s[20:21], v228, s52, v[4:5]
	v_lshl_add_u32 v2, v202, 2, 0
	ds_write_b128 v2, v[198:201]
	s_waitcnt vmcnt(2)
	v_lshlrev_b32_e32 v2, 16, v238
	v_rcp_f32_e32 v198, v2
	v_and_b32_e32 v2, 0xffff0000, v238
	v_rcp_f32_e32 v199, v2
	v_lshlrev_b32_e32 v2, 16, v239
	v_rcp_f32_e32 v202, v2
	v_and_b32_e32 v2, 0xffff0000, v239
	v_rcp_f32_e32 v203, v2
	v_lshlrev_b32_e32 v200, 16, v246
	v_and_b32_e32 v201, 0xffff0000, v246
	v_pk_mul_f32 v[198:199], v[198:199], v[200:201]
	v_lshlrev_b32_e32 v200, 16, v247
	v_and_b32_e32 v201, 0xffff0000, v247
	v_pk_mul_f32 v[200:201], v[202:203], v[200:201]
	v_mad_u64_u32 v[202:203], s[20:21], v236, s52, v[4:5]
	v_lshl_add_u32 v2, v202, 2, 0
	ds_write_b128 v2, v[198:201]
	s_waitcnt vmcnt(0)
	v_lshlrev_b32_e32 v2, 16, v244
	v_rcp_f32_e32 v198, v2
	v_and_b32_e32 v2, 0xffff0000, v244
	v_rcp_f32_e32 v199, v2
	v_lshlrev_b32_e32 v2, 16, v245
	v_rcp_f32_e32 v202, v2
	v_and_b32_e32 v2, 0xffff0000, v245
	v_rcp_f32_e32 v203, v2
	v_lshlrev_b32_e32 v200, 16, v242
	v_and_b32_e32 v201, 0xffff0000, v242
	v_pk_mul_f32 v[198:199], v[198:199], v[200:201]
	v_lshlrev_b32_e32 v200, 16, v243
	v_and_b32_e32 v201, 0xffff0000, v243
	v_pk_mul_f32 v[200:201], v[202:203], v[200:201]
	v_mad_u64_u32 v[202:203], s[20:21], v240, s52, v[4:5]
	v_lshl_add_u32 v2, v202, 2, 0
	ds_write_b128 v2, v[198:201]
	v_add_lshl_u32 v2, v5, v134, 2
	v_add3_u32 v2, 0, v135, v2
	s_waitcnt lgkmcnt(0)
	s_barrier
; __device__ __forceinline__ void phase4(const Params& p, char* shm) {
;     ...
;         for (int i = 0; i < 8; ++i) { const int id = tid + (b8 * 8 + i) * NTHR, row = id >> 6, c = id & 63;
;           ga[i] = *reinterpret_cast<const u32x2*>(gsrc + (size_t)row * 4096 + c * 4);
;           gb[i] = *reinterpret_cast<const u32x2*>(gsrc + (size_t)row * 4096 + 2048 + c * 4); }
;     ...
;       __syncthreads();
; #pragma unroll
;       for (int bj = 0; bj < 2; ++bj)
; #pragma unroll
;         for (int m = 0; m < 4; ++m)
; #pragma unroll
;           for (int n = 0; n < 2; ++n) acc[ai][bj][m][n] *= *(const f32x4*)(cfb + CF_OFF(bj, m, n));
	ds_read_b128 v[134:137], v2
	ds_read_b128 v[138:141], v2 offset:64
	ds_read_b128 v[142:145], v2 offset:16640
	ds_read_b128 v[146:149], v2 offset:33792
	s_waitcnt lgkmcnt(3)
	v_pk_mul_f32 v[132:133], v[132:133], v[136:137]
	v_pk_mul_f32 v[130:131], v[130:131], v[134:135]
	s_waitcnt lgkmcnt(2)
	v_pk_mul_f32 v[128:129], v[128:129], v[140:141]
	ds_read_b128 v[134:137], v2 offset:16704
	v_pk_mul_f32 v[126:127], v[126:127], v[138:139]
	ds_read_b128 v[138:141], v2 offset:33280
	s_waitcnt lgkmcnt(3)
	v_pk_mul_f32 v[124:125], v[124:125], v[144:145]
	v_pk_mul_f32 v[122:123], v[122:123], v[142:143]
	s_waitcnt lgkmcnt(1)
	v_pk_mul_f32 v[120:121], v[120:121], v[136:137]
	ds_read_b128 v[142:145], v2 offset:33344
	v_pk_mul_f32 v[118:119], v[118:119], v[134:135]
	s_waitcnt lgkmcnt(1)
	v_pk_mul_f32 v[116:117], v[116:117], v[140:141]
	ds_read_b128 v[134:137], v2 offset:49920
	v_pk_mul_f32 v[114:115], v[114:115], v[138:139]
	ds_read_b128 v[138:141], v2 offset:49984
	s_waitcnt lgkmcnt(2)
	v_pk_mul_f32 v[112:113], v[112:113], v[144:145]
	v_pk_mul_f32 v[110:111], v[110:111], v[142:143]
	ds_read_b128 v[142:145], v2 offset:512
	s_waitcnt lgkmcnt(2)
	v_pk_mul_f32 v[108:109], v[108:109], v[136:137]
	s_waitcnt lgkmcnt(1)
	v_pk_mul_f32 v[104:105], v[104:105], v[140:141]
	v_pk_mul_f32 v[102:103], v[102:103], v[138:139]
	ds_read_b128 v[138:141], v2 offset:17152
	v_pk_mul_f32 v[106:107], v[106:107], v[134:135]
	ds_read_b128 v[134:137], v2 offset:576
	s_waitcnt lgkmcnt(2)
	v_pk_mul_f32 v[100:101], v[100:101], v[144:145]
	v_pk_mul_f32 v[98:99], v[98:99], v[142:143]
	ds_read_b128 v[142:145], v2 offset:17216
	s_waitcnt lgkmcnt(2)
	v_pk_mul_f32 v[92:93], v[92:93], v[140:141]
	v_pk_mul_f32 v[90:91], v[90:91], v[138:139]
	ds_read_b128 v[138:141], v2 offset:33856
	s_waitcnt lgkmcnt(2)
	v_pk_mul_f32 v[96:97], v[96:97], v[136:137]
	v_pk_mul_f32 v[94:95], v[94:95], v[134:135]
	ds_read_b128 v[134:137], v2 offset:50432
	v_pk_mul_f32 v[82:83], v[82:83], v[146:147]
	s_waitcnt lgkmcnt(1)
	v_pk_mul_f32 v[80:81], v[80:81], v[140:141]
	v_pk_mul_f32 v[78:79], v[78:79], v[138:139]
	ds_read_b128 v[138:141], v2 offset:50496
	s_waitcnt lgkmcnt(0)
	s_barrier
	v_pk_mul_f32 v[76:77], v[76:77], v[136:137]
	v_and_b32_e32 v2, 15, v187
	v_lshrrev_b32_e32 v4, 2, v187
	v_and_or_b32 v2, v4, s51, v2
	v_mul_lo_u32 v5, v2, s52
	v_lshrrev_b32_e32 v2, 1, v187
	v_ashrrev_i32_e32 v146, 6, v187
	v_and_b32_e32 v136, 0x60, v2
	v_lshlrev_b32_e32 v2, 2, v187
	v_ashrrev_i32_e32 v147, 31, v146
	v_pk_mul_f32 v[86:87], v[86:87], v[142:143]
	v_and_b32_e32 v4, 0xfc, v2
	v_lshlrev_b64 v[142:143], 13, v[146:147]
	v_lshl_add_u64 v[142:143], s[14:15], 0, v[142:143]
	v_lshlrev_b32_e32 v2, 1, v4
	v_lshl_add_u64 v[142:143], v[142:143], 0, v[2:3]
	v_pk_mul_f32 v[88:89], v[88:89], v[144:145]
	v_add_co_u32_e32 v144, vcc, s49, v142
	v_pk_mul_f32 v[84:85], v[84:85], v[148:149]
	s_nop 0
	v_addc_co_u32_e32 v145, vcc, 0, v143, vcc
	global_load_dwordx2 v[148:149], v[142:143], off
	s_nop 0
	global_load_dwordx2 v[142:143], v[144:145], off
	v_add_u32_e32 v144, 0x200, v187
	v_ashrrev_i32_e32 v150, 6, v144
	v_ashrrev_i32_e32 v151, 31, v150
	v_lshlrev_b64 v[144:145], 13, v[150:151]
	v_lshl_add_u64 v[144:145], s[14:15], 0, v[144:145]
	v_lshl_add_u64 v[144:145], v[144:145], 0, v[2:3]
	v_add_co_u32_e32 v152, vcc, s49, v144
	v_add_u32_e32 v147, 0x600, v187
	s_nop 0
	v_addc_co_u32_e32 v153, vcc, 0, v145, vcc
	global_load_dwordx2 v[154:155], v[144:145], off
	s_nop 0
	global_load_dwordx2 v[152:153], v[152:153], off
	v_add_u32_e32 v144, 0x400, v187
	v_ashrrev_i32_e32 v156, 6, v144
	v_ashrrev_i32_e32 v157, 31, v156
	v_lshlrev_b64 v[144:145], 13, v[156:157]
	v_ashrrev_i32_e32 v160, 6, v147
	v_lshl_add_u64 v[144:145], s[14:15], 0, v[144:145]
	v_ashrrev_i32_e32 v161, 31, v160
	v_lshl_add_u64 v[144:145], v[144:145], 0, v[2:3]
	v_lshlrev_b64 v[162:163], 13, v[160:161]
	v_add_co_u32_e32 v158, vcc, s49, v144
	v_lshl_add_u64 v[162:163], s[14:15], 0, v[162:163]
	s_nop 0
	v_addc_co_u32_e32 v159, vcc, 0, v145, vcc
	v_lshl_add_u64 v[162:163], v[162:163], 0, v[2:3]
	v_add_co_u32_e32 v164, vcc, s49, v162
	v_add_u32_e32 v147, 0xa00, v187
	s_nop 0
	v_addc_co_u32_e32 v165, vcc, 0, v163, vcc
	global_load_dwordx2 v[166:167], v[144:145], off
	s_nop 0
	global_load_dwordx2 v[158:159], v[158:159], off
	s_nop 0
	global_load_dwordx2 v[162:163], v[162:163], off
	s_nop 0
	global_load_dwordx2 v[164:165], v[164:165], off
	v_add_u32_e32 v144, 0x800, v187
	v_ashrrev_i32_e32 v168, 6, v144
	v_ashrrev_i32_e32 v169, 31, v168
	v_lshlrev_b64 v[144:145], 13, v[168:169]
	v_ashrrev_i32_e32 v172, 6, v147
	v_lshl_add_u64 v[144:145], s[14:15], 0, v[144:145]
	v_ashrrev_i32_e32 v173, 31, v172
	v_lshl_add_u64 v[144:145], v[144:145], 0, v[2:3]
	v_lshlrev_b64 v[174:175], 13, v[172:173]
	v_add_co_u32_e32 v170, vcc, s49, v144
	v_lshl_add_u64 v[174:175], s[14:15], 0, v[174:175]
	s_nop 0
	v_addc_co_u32_e32 v171, vcc, 0, v145, vcc
	v_lshl_add_u64 v[174:175], v[174:175], 0, v[2:3]
	v_add_co_u32_e32 v176, vcc, s49, v174
	v_add_u32_e32 v147, 0xe00, v187
	s_nop 0
	v_addc_co_u32_e32 v177, vcc, 0, v175, vcc
	global_load_dwordx2 v[178:179], v[144:145], off
	s_nop 0
	global_load_dwordx2 v[170:171], v[170:171], off
	s_nop 0
	global_load_dwordx2 v[174:175], v[174:175], off
	s_nop 0
	global_load_dwordx2 v[176:177], v[176:177], off
	v_add_u32_e32 v144, 0xc00, v187
	v_ashrrev_i32_e32 v180, 6, v144
	v_ashrrev_i32_e32 v181, 31, v180
	v_lshlrev_b64 v[144:145], 13, v[180:181]
	v_ashrrev_i32_e32 v184, 6, v147
	v_lshl_add_u64 v[144:145], s[14:15], 0, v[144:145]
	v_ashrrev_i32_e32 v185, 31, v184
	v_lshl_add_u64 v[144:145], v[144:145], 0, v[2:3]
	v_lshlrev_b64 v[188:189], 13, v[184:185]
	v_add_co_u32_e32 v182, vcc, s49, v144
; __device__ __forceinline__ float bflo(unsigned v) { return __uint_as_float(v << 16); }
; __device__ __forceinline__ float bfhi(unsigned v) { return __uint_as_float(v & 0xffff0000u); }
; __device__ __forceinline__ void phase4(const Params& p, char* shm) {
;     ...
;         for (int i = 0; i < 8; ++i) { const int id = tid + (b8 * 8 + i) * NTHR, row = id >> 6, c = id & 63;
;           ga[i] = *reinterpret_cast<const u32x2*>(gsrc + (size_t)row * 4096 + c * 4);
;           gb[i] = *reinterpret_cast<const u32x2*>(gsrc + (size_t)row * 4096 + 2048 + c * 4); }
; #pragma unroll
;         for (int i = 0; i < 8; ++i) { const int id = tid + (b8 * 8 + i) * NTHR, row = id >> 6, c = id & 63;
;           f32x4 rt = { bflo(ga[i][0]) * __builtin_amdgcn_rcpf(bflo(gb[i][0])), bfhi(ga[i][0]) * __builtin_amdgcn_rcpf(bfhi(gb[i][0])),
;                        bflo(ga[i][1]) * __builtin_amdgcn_rcpf(bflo(gb[i][1])), bfhi(ga[i][1]) * __builtin_amdgcn_rcpf(bfhi(gb[i][1])) };
;           *reinterpret_cast<f32x4*>(shm + (row * CF_LD + c * 4) * 4) = rt; }
	v_lshl_add_u64 v[188:189], s[14:15], 0, v[188:189]
	s_nop 0
	v_addc_co_u32_e32 v183, vcc, 0, v145, vcc
	v_lshl_add_u64 v[188:189], v[188:189], 0, v[2:3]
	v_add_co_u32_e32 v190, vcc, s49, v188
	v_mad_u64_u32 v[146:147], s[20:21], v146, s52, v[4:5]
	s_nop 0
	v_addc_co_u32_e32 v191, vcc, 0, v189, vcc
	global_load_dwordx2 v[192:193], v[144:145], off
	s_nop 0
	global_load_dwordx2 v[182:183], v[182:183], off
	s_nop 0
	global_load_dwordx2 v[188:189], v[188:189], off
	s_nop 0
	global_load_dwordx2 v[190:191], v[190:191], off
	v_add_u32_e32 v204, 0x1000, v187
	v_ashrrev_i32_e32 v208, 6, v204
	v_ashrrev_i32_e32 v209, 31, v208
	v_lshlrev_b64 v[204:205], 13, v[208:209]
	v_lshl_add_u64 v[204:205], s[14:15], 0, v[204:205]
	v_lshl_add_u64 v[204:205], v[204:205], 0, v[2:3]
	v_add_co_u32_e32 v206, vcc, s49, v204
	v_add_u32_e32 v209, 0x1600, v187
	s_nop 0
	v_addc_co_u32_e32 v207, vcc, 0, v205, vcc
	global_load_dwordx2 v[210:211], v[204:205], off
	s_nop 0
	global_load_dwordx2 v[204:205], v[206:207], off
	v_add_u32_e32 v206, 0x1200, v187
	v_ashrrev_i32_e32 v212, 6, v206
	v_ashrrev_i32_e32 v213, 31, v212
	v_lshlrev_b64 v[206:207], 13, v[212:213]
	v_lshl_add_u64 v[206:207], s[14:15], 0, v[206:207]
	v_lshl_add_u64 v[206:207], v[206:207], 0, v[2:3]
	v_add_co_u32_e32 v214, vcc, s49, v206
	v_ashrrev_i32_e32 v222, 6, v209
	s_nop 0
	v_addc_co_u32_e32 v215, vcc, 0, v207, vcc
	global_load_dwordx2 v[216:217], v[206:207], off
	s_nop 0
	global_load_dwordx2 v[214:215], v[214:215], off
	v_add_u32_e32 v206, 0x1400, v187
	v_ashrrev_i32_e32 v218, 6, v206
	v_ashrrev_i32_e32 v219, 31, v218
	v_lshlrev_b64 v[206:207], 13, v[218:219]
	v_lshl_add_u64 v[206:207], s[14:15], 0, v[206:207]
	v_ashrrev_i32_e32 v223, 31, v222
	v_lshl_add_u64 v[206:207], v[206:207], 0, v[2:3]
	v_lshlrev_b64 v[224:225], 13, v[222:223]
	v_add_co_u32_e32 v220, vcc, s49, v206
	v_lshl_add_u64 v[224:225], s[14:15], 0, v[224:225]
	s_nop 0
	v_addc_co_u32_e32 v221, vcc, 0, v207, vcc
	v_lshl_add_u64 v[224:225], v[224:225], 0, v[2:3]
	v_add_co_u32_e32 v226, vcc, s49, v224
	v_add_u32_e32 v209, 0x1a00, v187
	s_nop 0
	v_addc_co_u32_e32 v227, vcc, 0, v225, vcc
	global_load_dwordx2 v[228:229], v[206:207], off
	s_nop 0
	global_load_dwordx2 v[220:221], v[220:221], off
	s_nop 0
	global_load_dwordx2 v[224:225], v[224:225], off
	s_nop 0
	global_load_dwordx2 v[226:227], v[226:227], off
	v_add_u32_e32 v206, 0x1800, v187
	v_ashrrev_i32_e32 v230, 6, v206
	v_ashrrev_i32_e32 v231, 31, v230
	v_lshlrev_b64 v[206:207], 13, v[230:231]
	v_ashrrev_i32_e32 v234, 6, v209
	v_lshl_add_u64 v[206:207], s[14:15], 0, v[206:207]
	v_ashrrev_i32_e32 v235, 31, v234
	v_lshl_add_u64 v[206:207], v[206:207], 0, v[2:3]
	v_lshlrev_b64 v[236:237], 13, v[234:235]
	v_add_co_u32_e32 v232, vcc, s49, v206
	v_lshl_add_u64 v[236:237], s[14:15], 0, v[236:237]
	s_nop 0
	v_addc_co_u32_e32 v233, vcc, 0, v207, vcc
	v_lshl_add_u64 v[236:237], v[236:237], 0, v[2:3]
	v_add_co_u32_e32 v238, vcc, s49, v236
	v_add_u32_e32 v209, 0x1e00, v187
	s_nop 0
	v_addc_co_u32_e32 v239, vcc, 0, v237, vcc
	global_load_dwordx2 v[240:241], v[206:207], off
	s_nop 0
	global_load_dwordx2 v[232:233], v[232:233], off
	s_nop 0
	global_load_dwordx2 v[236:237], v[236:237], off
	s_nop 0
	global_load_dwordx2 v[238:239], v[238:239], off
	v_add_u32_e32 v206, 0x1c00, v187
	v_ashrrev_i32_e32 v242, 6, v206
	v_ashrrev_i32_e32 v243, 31, v242
	v_lshlrev_b64 v[206:207], 13, v[242:243]
	v_ashrrev_i32_e32 v246, 6, v209
	v_lshl_add_u64 v[206:207], s[14:15], 0, v[206:207]
	v_ashrrev_i32_e32 v247, 31, v246
	v_lshl_add_u64 v[206:207], v[206:207], 0, v[2:3]
	v_lshlrev_b64 v[248:249], 13, v[246:247]
	v_add_co_u32_e32 v244, vcc, s49, v206
	v_lshl_add_u64 v[248:249], s[14:15], 0, v[248:249]
	s_nop 0
	v_addc_co_u32_e32 v245, vcc, 0, v207, vcc
	v_lshl_add_u64 v[248:249], v[248:249], 0, v[2:3]
	v_add_co_u32_e32 v250, vcc, s49, v248
	v_mad_u64_u32 v[208:209], s[20:21], v208, s52, v[4:5]
	s_nop 0
	v_addc_co_u32_e32 v251, vcc, 0, v249, vcc
	global_load_dwordx2 v[252:253], v[206:207], off
	s_nop 0
	global_load_dwordx2 v[244:245], v[244:245], off
	s_nop 0
	global_load_dwordx2 v[248:249], v[248:249], off
	s_nop 0
	global_load_dwordx2 v[250:251], v[250:251], off
	v_lshl_add_u32 v146, v146, 2, 0
	v_and_b32_e32 v137, 48, v187
	s_waitcnt vmcnt(31)
	v_lshlrev_b32_e32 v194, 16, v148
	s_waitcnt vmcnt(30)
	v_lshlrev_b32_e32 v144, 16, v142
	v_and_b32_e32 v142, 0xffff0000, v142
	v_rcp_f32_e32 v145, v142
	v_lshlrev_b32_e32 v142, 16, v143
	v_rcp_f32_e32 v144, v144
	v_rcp_f32_e32 v196, v142
	v_and_b32_e32 v142, 0xffff0000, v143
	v_rcp_f32_e32 v197, v142
	v_and_b32_e32 v195, 0xffff0000, v148
	v_pk_mul_f32 v[142:143], v[144:145], v[194:195]
	v_lshlrev_b32_e32 v144, 16, v149
	v_and_b32_e32 v145, 0xffff0000, v149
	v_pk_mul_f32 v[144:145], v[196:197], v[144:145]
	ds_write_b128 v146, v[142:145]
	s_waitcnt vmcnt(28)
	v_lshlrev_b32_e32 v142, 16, v152
	v_and_b32_e32 v143, 0xffff0000, v152
	v_rcp_f32_e32 v142, v142
	v_rcp_f32_e32 v143, v143
	v_lshlrev_b32_e32 v146, 16, v153
	v_and_b32_e32 v147, 0xffff0000, v153
	v_rcp_f32_e32 v146, v146
	v_rcp_f32_e32 v147, v147
	v_lshlrev_b32_e32 v144, 16, v154
	v_and_b32_e32 v145, 0xffff0000, v154
	v_pk_mul_f32 v[142:143], v[142:143], v[144:145]
	v_lshlrev_b32_e32 v144, 16, v155
	v_and_b32_e32 v145, 0xffff0000, v155
	v_pk_mul_f32 v[144:145], v[146:147], v[144:145]
	v_mad_u64_u32 v[146:147], s[20:21], v150, s52, v[4:5]
	v_lshl_add_u32 v146, v146, 2, 0
	ds_write_b128 v146, v[142:145]
	s_waitcnt vmcnt(26)
; __device__ __forceinline__ float bflo(unsigned v) { return __uint_as_float(v << 16); }
; __device__ __forceinline__ float bfhi(unsigned v) { return __uint_as_float(v & 0xffff0000u); }
; __device__ __forceinline__ void phase4(const Params& p, char* shm) {
;     ...
;         for (int i = 0; i < 8; ++i) { const int id = tid + (b8 * 8 + i) * NTHR, row = id >> 6, c = id & 63;
;           f32x4 rt = { bflo(ga[i][0]) * __builtin_amdgcn_rcpf(bflo(gb[i][0])), bfhi(ga[i][0]) * __builtin_amdgcn_rcpf(bfhi(gb[i][0])),
;                        bflo(ga[i][1]) * __builtin_amdgcn_rcpf(bflo(gb[i][1])), bfhi(ga[i][1]) * __builtin_amdgcn_rcpf(bfhi(gb[i][1])) };
;           *reinterpret_cast<f32x4*>(shm + (row * CF_LD + c * 4) * 4) = rt; }
	v_lshlrev_b32_e32 v142, 16, v158
	v_and_b32_e32 v143, 0xffff0000, v158
	v_rcp_f32_e32 v142, v142
	v_rcp_f32_e32 v143, v143
	v_lshlrev_b32_e32 v146, 16, v159
	v_and_b32_e32 v147, 0xffff0000, v159
	v_rcp_f32_e32 v146, v146
	v_rcp_f32_e32 v147, v147
	v_lshlrev_b32_e32 v144, 16, v166
	v_and_b32_e32 v145, 0xffff0000, v166
	v_pk_mul_f32 v[142:143], v[142:143], v[144:145]
	v_lshlrev_b32_e32 v144, 16, v167
	v_and_b32_e32 v145, 0xffff0000, v167
	v_pk_mul_f32 v[144:145], v[146:147], v[144:145]
	v_mad_u64_u32 v[146:147], s[20:21], v156, s52, v[4:5]
	v_lshl_add_u32 v146, v146, 2, 0
	ds_write_b128 v146, v[142:145]
	s_waitcnt vmcnt(24)
	v_lshlrev_b32_e32 v142, 16, v164
	v_and_b32_e32 v143, 0xffff0000, v164
	v_rcp_f32_e32 v142, v142
	v_rcp_f32_e32 v143, v143
	v_lshlrev_b32_e32 v146, 16, v165
	v_and_b32_e32 v147, 0xffff0000, v165
	v_rcp_f32_e32 v146, v146
	v_rcp_f32_e32 v147, v147
	v_lshlrev_b32_e32 v144, 16, v162
	v_and_b32_e32 v145, 0xffff0000, v162
	v_pk_mul_f32 v[142:143], v[142:143], v[144:145]
	v_lshlrev_b32_e32 v144, 16, v163
	v_and_b32_e32 v145, 0xffff0000, v163
	v_pk_mul_f32 v[144:145], v[146:147], v[144:145]
	v_mad_u64_u32 v[146:147], s[20:21], v160, s52, v[4:5]
	v_lshl_add_u32 v146, v146, 2, 0
	ds_write_b128 v146, v[142:145]
	s_waitcnt vmcnt(22)
	v_lshlrev_b32_e32 v142, 16, v170
	v_and_b32_e32 v143, 0xffff0000, v170
	v_rcp_f32_e32 v142, v142
	v_rcp_f32_e32 v143, v143
	v_lshlrev_b32_e32 v146, 16, v171
	v_and_b32_e32 v147, 0xffff0000, v171
	v_rcp_f32_e32 v146, v146
	v_rcp_f32_e32 v147, v147
	v_lshlrev_b32_e32 v144, 16, v178
	v_and_b32_e32 v145, 0xffff0000, v178
	v_pk_mul_f32 v[142:143], v[142:143], v[144:145]
	v_lshlrev_b32_e32 v144, 16, v179
	v_and_b32_e32 v145, 0xffff0000, v179
	v_pk_mul_f32 v[144:145], v[146:147], v[144:145]
	v_mad_u64_u32 v[146:147], s[20:21], v168, s52, v[4:5]
	v_lshl_add_u32 v146, v146, 2, 0
	ds_write_b128 v146, v[142:145]
	s_waitcnt vmcnt(20)
	v_lshlrev_b32_e32 v142, 16, v176
	v_and_b32_e32 v143, 0xffff0000, v176
	v_rcp_f32_e32 v142, v142
	v_rcp_f32_e32 v143, v143
	v_lshlrev_b32_e32 v146, 16, v177
	v_and_b32_e32 v147, 0xffff0000, v177
	v_rcp_f32_e32 v146, v146
	v_rcp_f32_e32 v147, v147
	v_lshlrev_b32_e32 v144, 16, v174
	v_and_b32_e32 v145, 0xffff0000, v174
	v_pk_mul_f32 v[142:143], v[142:143], v[144:145]
	v_lshlrev_b32_e32 v144, 16, v175
	v_and_b32_e32 v145, 0xffff0000, v175
	v_pk_mul_f32 v[144:145], v[146:147], v[144:145]
	v_mad_u64_u32 v[146:147], s[20:21], v172, s52, v[4:5]
	v_lshl_add_u32 v146, v146, 2, 0
	ds_write_b128 v146, v[142:145]
	s_waitcnt vmcnt(18)
	v_lshlrev_b32_e32 v142, 16, v182
	v_and_b32_e32 v143, 0xffff0000, v182
	v_rcp_f32_e32 v142, v142
	v_rcp_f32_e32 v143, v143
	v_lshlrev_b32_e32 v146, 16, v183
	v_and_b32_e32 v147, 0xffff0000, v183
	v_rcp_f32_e32 v146, v146
	v_rcp_f32_e32 v147, v147
	v_lshlrev_b32_e32 v144, 16, v192
	v_and_b32_e32 v145, 0xffff0000, v192
	v_pk_mul_f32 v[142:143], v[142:143], v[144:145]
	v_lshlrev_b32_e32 v144, 16, v193
	v_and_b32_e32 v145, 0xffff0000, v193
	v_pk_mul_f32 v[144:145], v[146:147], v[144:145]
	v_mad_u64_u32 v[146:147], s[20:21], v180, s52, v[4:5]
	v_lshl_add_u32 v146, v146, 2, 0
	ds_write_b128 v146, v[142:145]
	s_waitcnt vmcnt(16)
	v_lshlrev_b32_e32 v142, 16, v190
	v_and_b32_e32 v143, 0xffff0000, v190
	v_rcp_f32_e32 v142, v142
	v_rcp_f32_e32 v143, v143
	v_lshlrev_b32_e32 v146, 16, v191
	v_and_b32_e32 v147, 0xffff0000, v191
	v_rcp_f32_e32 v146, v146
	v_rcp_f32_e32 v147, v147
	v_lshlrev_b32_e32 v144, 16, v188
	v_and_b32_e32 v145, 0xffff0000, v188
	v_pk_mul_f32 v[142:143], v[142:143], v[144:145]
	v_lshlrev_b32_e32 v144, 16, v189
	v_and_b32_e32 v145, 0xffff0000, v189
	v_pk_mul_f32 v[144:145], v[146:147], v[144:145]
	v_mad_u64_u32 v[146:147], s[20:21], v184, s52, v[4:5]
	v_lshl_add_u32 v146, v146, 2, 0
	ds_write_b128 v146, v[142:145]
	v_pk_mul_f32 v[74:75], v[74:75], v[134:135]
	v_pk_mul_f32 v[72:73], v[72:73], v[140:141]
	v_pk_mul_f32 v[70:71], v[70:71], v[138:139]
	s_waitcnt vmcnt(15)
	v_lshlrev_b32_e32 v194, 16, v210
	s_waitcnt vmcnt(14)
	v_lshlrev_b32_e32 v2, 16, v204
	v_rcp_f32_e32 v206, v2
	v_and_b32_e32 v2, 0xffff0000, v204
	v_rcp_f32_e32 v207, v2
	v_lshlrev_b32_e32 v2, 16, v205
	v_rcp_f32_e32 v196, v2
	v_and_b32_e32 v2, 0xffff0000, v205
	v_rcp_f32_e32 v197, v2
	v_and_b32_e32 v195, 0xffff0000, v210
	v_pk_mul_f32 v[204:205], v[206:207], v[194:195]
	v_lshlrev_b32_e32 v206, 16, v211
	v_and_b32_e32 v207, 0xffff0000, v211
	v_pk_mul_f32 v[206:207], v[196:197], v[206:207]
	v_lshl_add_u32 v2, v208, 2, 0
	ds_write_b128 v2, v[204:207]
	s_waitcnt vmcnt(12)
	v_lshlrev_b32_e32 v2, 16, v214
	v_rcp_f32_e32 v204, v2
	v_and_b32_e32 v2, 0xffff0000, v214
	v_rcp_f32_e32 v205, v2
	v_lshlrev_b32_e32 v2, 16, v215
	v_rcp_f32_e32 v208, v2
	v_and_b32_e32 v2, 0xffff0000, v215
	v_rcp_f32_e32 v209, v2
	v_lshlrev_b32_e32 v206, 16, v216
	v_and_b32_e32 v207, 0xffff0000, v216
	v_pk_mul_f32 v[204:205], v[204:205], v[206:207]
	v_lshlrev_b32_e32 v206, 16, v217
	v_and_b32_e32 v207, 0xffff0000, v217
	v_pk_mul_f32 v[206:207], v[208:209], v[206:207]
	v_mad_u64_u32 v[208:209], s[20:21], v212, s52, v[4:5]
	v_lshl_add_u32 v2, v208, 2, 0
	ds_write_b128 v2, v[204:207]
	s_waitcnt vmcnt(10)
	v_lshlrev_b32_e32 v2, 16, v220
	v_rcp_f32_e32 v204, v2
	v_and_b32_e32 v2, 0xffff0000, v220
	v_rcp_f32_e32 v205, v2
	v_lshlrev_b32_e32 v2, 16, v221
	v_rcp_f32_e32 v208, v2
	v_and_b32_e32 v2, 0xffff0000, v221
	v_rcp_f32_e32 v209, v2
	v_lshlrev_b32_e32 v206, 16, v228
	v_and_b32_e32 v207, 0xffff0000, v228
	v_pk_mul_f32 v[204:205], v[204:205], v[206:207]
	v_lshlrev_b32_e32 v206, 16, v229
	v_and_b32_e32 v207, 0xffff0000, v229
	v_pk_mul_f32 v[206:207], v[208:209], v[206:207]
	v_mad_u64_u32 v[208:209], s[20:21], v218, s52, v[4:5]
	v_lshl_add_u32 v2, v208, 2, 0
	ds_write_b128 v2, v[204:207]
	s_waitcnt vmcnt(8)
; __device__ __forceinline__ float bflo(unsigned v) { return __uint_as_float(v << 16); }
; __device__ __forceinline__ float bfhi(unsigned v) { return __uint_as_float(v & 0xffff0000u); }
; __device__ __forceinline__ void phase4(const Params& p, char* shm) {
;     ...
;         for (int i = 0; i < 8; ++i) { const int id = tid + (b8 * 8 + i) * NTHR, row = id >> 6, c = id & 63;
;           f32x4 rt = { bflo(ga[i][0]) * __builtin_amdgcn_rcpf(bflo(gb[i][0])), bfhi(ga[i][0]) * __builtin_amdgcn_rcpf(bfhi(gb[i][0])),
;                        bflo(ga[i][1]) * __builtin_amdgcn_rcpf(bflo(gb[i][1])), bfhi(ga[i][1]) * __builtin_amdgcn_rcpf(bfhi(gb[i][1])) };
;           *reinterpret_cast<f32x4*>(shm + (row * CF_LD + c * 4) * 4) = rt; }
;       }
;       __syncthreads();
; #pragma unroll
;       for (int bj = 0; bj < 2; ++bj)
; #pragma unroll
;         for (int m = 0; m < 4; ++m)
; #pragma unroll
;           for (int n = 0; n < 2; ++n) acc[ai][bj][m][n] *= *(const f32x4*)(cfb + CF_OFF(bj, m, n));
;       __syncthreads();
	v_lshlrev_b32_e32 v2, 16, v226
	v_rcp_f32_e32 v204, v2
	v_and_b32_e32 v2, 0xffff0000, v226
	v_rcp_f32_e32 v205, v2
	v_lshlrev_b32_e32 v2, 16, v227
	v_rcp_f32_e32 v208, v2
	v_and_b32_e32 v2, 0xffff0000, v227
	v_rcp_f32_e32 v209, v2
	v_lshlrev_b32_e32 v206, 16, v224
	v_and_b32_e32 v207, 0xffff0000, v224
	v_pk_mul_f32 v[204:205], v[204:205], v[206:207]
	v_lshlrev_b32_e32 v206, 16, v225
	v_and_b32_e32 v207, 0xffff0000, v225
	v_pk_mul_f32 v[206:207], v[208:209], v[206:207]
	v_mad_u64_u32 v[208:209], s[20:21], v222, s52, v[4:5]
	v_lshl_add_u32 v2, v208, 2, 0
	ds_write_b128 v2, v[204:207]
	s_waitcnt vmcnt(6)
	v_lshlrev_b32_e32 v2, 16, v232
	v_rcp_f32_e32 v204, v2
	v_and_b32_e32 v2, 0xffff0000, v232
	v_rcp_f32_e32 v205, v2
	v_lshlrev_b32_e32 v2, 16, v233
	v_rcp_f32_e32 v208, v2
	v_and_b32_e32 v2, 0xffff0000, v233
	v_rcp_f32_e32 v209, v2
	v_lshlrev_b32_e32 v206, 16, v240
	v_and_b32_e32 v207, 0xffff0000, v240
	v_pk_mul_f32 v[204:205], v[204:205], v[206:207]
	v_lshlrev_b32_e32 v206, 16, v241
	v_and_b32_e32 v207, 0xffff0000, v241
	v_pk_mul_f32 v[206:207], v[208:209], v[206:207]
	v_mad_u64_u32 v[208:209], s[20:21], v230, s52, v[4:5]
	v_lshl_add_u32 v2, v208, 2, 0
	ds_write_b128 v2, v[204:207]
	s_waitcnt vmcnt(4)
	v_lshlrev_b32_e32 v2, 16, v238
	v_rcp_f32_e32 v204, v2
	v_and_b32_e32 v2, 0xffff0000, v238
	v_rcp_f32_e32 v205, v2
	v_lshlrev_b32_e32 v2, 16, v239
	v_rcp_f32_e32 v208, v2
	v_and_b32_e32 v2, 0xffff0000, v239
	v_rcp_f32_e32 v209, v2
	v_lshlrev_b32_e32 v206, 16, v236
	v_and_b32_e32 v207, 0xffff0000, v236
	v_pk_mul_f32 v[204:205], v[204:205], v[206:207]
	v_lshlrev_b32_e32 v206, 16, v237
	v_and_b32_e32 v207, 0xffff0000, v237
	v_pk_mul_f32 v[206:207], v[208:209], v[206:207]
	v_mad_u64_u32 v[208:209], s[20:21], v234, s52, v[4:5]
	v_lshl_add_u32 v2, v208, 2, 0
	ds_write_b128 v2, v[204:207]
	s_waitcnt vmcnt(2)
	v_lshlrev_b32_e32 v2, 16, v244
	v_rcp_f32_e32 v204, v2
	v_and_b32_e32 v2, 0xffff0000, v244
	v_rcp_f32_e32 v205, v2
	v_lshlrev_b32_e32 v2, 16, v245
	v_rcp_f32_e32 v208, v2
	v_and_b32_e32 v2, 0xffff0000, v245
	v_rcp_f32_e32 v209, v2
	v_lshlrev_b32_e32 v206, 16, v252
	v_and_b32_e32 v207, 0xffff0000, v252
	v_pk_mul_f32 v[204:205], v[204:205], v[206:207]
	v_lshlrev_b32_e32 v206, 16, v253
	v_and_b32_e32 v207, 0xffff0000, v253
	v_pk_mul_f32 v[206:207], v[208:209], v[206:207]
	v_mad_u64_u32 v[208:209], s[20:21], v242, s52, v[4:5]
	v_lshl_add_u32 v2, v208, 2, 0
	ds_write_b128 v2, v[204:207]
	s_waitcnt vmcnt(0)
	v_lshlrev_b32_e32 v2, 16, v250
	v_rcp_f32_e32 v204, v2
	v_and_b32_e32 v2, 0xffff0000, v250
	v_rcp_f32_e32 v205, v2
	v_lshlrev_b32_e32 v2, 16, v251
	v_rcp_f32_e32 v208, v2
	v_and_b32_e32 v2, 0xffff0000, v251
	v_rcp_f32_e32 v209, v2
	v_lshlrev_b32_e32 v206, 16, v248
	v_and_b32_e32 v207, 0xffff0000, v248
	v_pk_mul_f32 v[204:205], v[204:205], v[206:207]
	v_lshlrev_b32_e32 v206, 16, v249
	v_and_b32_e32 v207, 0xffff0000, v249
	v_pk_mul_f32 v[206:207], v[208:209], v[206:207]
	v_mad_u64_u32 v[208:209], s[20:21], v246, s52, v[4:5]
	v_lshl_add_u32 v2, v208, 2, 0
	ds_write_b128 v2, v[204:207]
	v_add_lshl_u32 v2, v5, v136, 2
	v_add3_u32 v2, 0, v137, v2
	s_waitcnt lgkmcnt(0)
	s_barrier
	ds_read_b128 v[142:145], v2
	ds_read_b128 v[134:137], v2 offset:64
	ds_read_b128 v[138:141], v2 offset:16640
	s_waitcnt lgkmcnt(2)
	v_pk_mul_f32 v[68:69], v[68:69], v[144:145]
	v_pk_mul_f32 v[66:67], v[66:67], v[142:143]
	ds_read_b128 v[142:145], v2 offset:16704
	s_waitcnt lgkmcnt(2)
	v_pk_mul_f32 v[64:65], v[64:65], v[136:137]
	v_pk_mul_f32 v[62:63], v[62:63], v[134:135]
	s_waitcnt lgkmcnt(1)
	v_pk_mul_f32 v[60:61], v[60:61], v[140:141]
	ds_read_b128 v[134:137], v2 offset:33280
	v_pk_mul_f32 v[58:59], v[58:59], v[138:139]
	s_waitcnt lgkmcnt(1)
	v_pk_mul_f32 v[56:57], v[56:57], v[144:145]
	ds_read_b128 v[138:141], v2 offset:33344
	v_pk_mul_f32 v[54:55], v[54:55], v[142:143]
	ds_read_b128 v[142:145], v2 offset:49920
	s_waitcnt lgkmcnt(2)
	v_pk_mul_f32 v[52:53], v[52:53], v[136:137]
	v_pk_mul_f32 v[50:51], v[50:51], v[134:135]
	s_waitcnt lgkmcnt(1)
	v_pk_mul_f32 v[48:49], v[48:49], v[140:141]
	ds_read_b128 v[134:137], v2 offset:49984
	v_pk_mul_f32 v[46:47], v[46:47], v[138:139]
	s_waitcnt lgkmcnt(1)
	v_pk_mul_f32 v[44:45], v[44:45], v[144:145]
	ds_read_b128 v[138:141], v2 offset:512
	v_pk_mul_f32 v[42:43], v[42:43], v[142:143]
	ds_read_b128 v[142:145], v2 offset:576
	s_waitcnt lgkmcnt(2)
	v_pk_mul_f32 v[40:41], v[40:41], v[136:137]
	v_pk_mul_f32 v[38:39], v[38:39], v[134:135]
	s_waitcnt lgkmcnt(1)
	v_pk_mul_f32 v[36:37], v[36:37], v[140:141]
	ds_read_b128 v[134:137], v2 offset:17152
	v_pk_mul_f32 v[34:35], v[34:35], v[138:139]
	s_waitcnt lgkmcnt(1)
	v_pk_mul_f32 v[32:33], v[32:33], v[144:145]
	ds_read_b128 v[138:141], v2 offset:17216
	v_pk_mul_f32 v[30:31], v[30:31], v[142:143]
	ds_read_b128 v[142:145], v2 offset:33792
	s_waitcnt lgkmcnt(2)
	v_pk_mul_f32 v[28:29], v[28:29], v[136:137]
	v_pk_mul_f32 v[26:27], v[26:27], v[134:135]
	s_waitcnt lgkmcnt(1)
	v_pk_mul_f32 v[24:25], v[24:25], v[140:141]
	v_pk_mul_f32 v[22:23], v[22:23], v[138:139]
	ds_read_b128 v[134:137], v2 offset:33856
	s_waitcnt lgkmcnt(1)
	v_pk_mul_f32 v[20:21], v[20:21], v[144:145]
	ds_read_b128 v[138:141], v2 offset:50432
	v_pk_mul_f32 v[18:19], v[18:19], v[142:143]
	ds_read_b128 v[142:145], v2 offset:50496
	s_waitcnt lgkmcnt(2)
	v_pk_mul_f32 v[16:17], v[16:17], v[136:137]
	v_pk_mul_f32 v[14:15], v[14:15], v[134:135]
	s_waitcnt lgkmcnt(1)
	v_pk_mul_f32 v[12:13], v[12:13], v[140:141]
	v_pk_mul_f32 v[10:11], v[10:11], v[138:139]
	s_waitcnt lgkmcnt(0)
	v_pk_mul_f32 v[8:9], v[8:9], v[144:145]
	v_pk_mul_f32 v[6:7], v[6:7], v[142:143]
	s_barrier
	s_branch .LBB0_450
